# FFT stage 0: 4-deep per-wave LDS-DMA ring placed in the table area (table staging moved after stage 0, its load latency overlapped with the ring start)
# speedup vs baseline: 1.0123x; 1.0018x over previous
.LBB0_803:
	s_lshl_b32 s0, s4, 11
	s_and_b32 s7, s4, 31
	v_mov_b32_e32 v78, v0
	s_and_b32 s0, s0, 0x3800
	v_readlane_b32 s1, v252, 2
	s_add_u32 s0, s1, s0
	v_and_b32_e32 v80, 15, v78
	v_readlane_b32 s1, v252, 3
	s_addc_u32 s1, s1, 0
	v_lshlrev_b32_e32 v98, 7, v80
	s_waitcnt lgkmcnt(0)
	v_lshl_add_u64 v[2:3], s[0:1], 0, v[98:99]
	v_readlane_b32 s0, v251, 62
	v_lshlrev_b32_e32 v10, 4, v80
	v_mov_b32_e32 v11, v99
	v_readlane_b32 s1, v251, 63
	v_readlane_b32 s10, v254, 15
	v_ashrrev_i32_e32 v17, 4, v78
	v_bfe_u32 v81, v78, 4, 2
	v_lshl_add_u64 v[14:15], s[0:1], 0, v[10:11]
	v_add_u32_e32 v16, s10, v10
	v_lshlrev_b32_e32 v10, 7, v17
	v_lshlrev_b32_e32 v74, 4, v81
	v_mov_b32_e32 v75, v99
	v_ashrrev_i32_e32 v11, 31, v10
	v_lshl_add_u64 v[2:3], v[2:3], 0, v[74:75]
	v_lshl_add_u64 v[10:11], v[10:11], 1, v[14:15]
	global_load_dwordx4 v[6:9], v[2:3], off
	s_nop 0
	global_load_dwordx4 v[2:5], v[2:3], off offset:64
	v_mul_lo_u32 v17, v17, s31
	global_load_dwordx4 v[100:103], v[10:11], off
	v_add_u32_e32 v18, v16, v17
	v_add_u32_e32 v20, 0x200, v78
	v_readlane_b32 s11, v254, 16
	v_ashrrev_i32_e32 v82, 6, v78
	v_readlane_b32 s8, v252, 0
	v_readlane_b32 s9, v252, 1
	v_lshrrev_b32_e32 v83, 4, v78
	v_lshlrev_b32_e32 v79, 6, v80
	v_mov_b32_e32 v124, v18
	v_ashrrev_i32_e32 v18, 4, v20
	v_lshlrev_b32_e32 v10, 7, v18
	v_ashrrev_i32_e32 v11, 31, v10
	v_lshl_add_u64 v[10:11], v[10:11], 1, v[14:15]
	global_load_dwordx4 v[104:107], v[10:11], off
	v_mul_lo_u32 v21, v18, s31
	v_add_u32_e32 v18, v16, v21
	v_mov_b32_e32 v125, v18
	v_add_u32_e32 v10, 0x400, v78
	v_ashrrev_i32_e32 v18, 4, v10
	v_lshlrev_b32_e32 v10, 7, v18
	v_ashrrev_i32_e32 v11, 31, v10
	v_lshl_add_u64 v[10:11], v[10:11], 1, v[14:15]
	global_load_dwordx4 v[108:111], v[10:11], off
	v_mad_u64_u32 v[18:19], s[0:1], v18, s31, v[16:17]
	v_mov_b32_e32 v126, v18
	v_add_u32_e32 v10, 0x600, v78
	v_ashrrev_i32_e32 v18, 4, v10
	v_lshlrev_b32_e32 v10, 7, v18
	v_ashrrev_i32_e32 v11, 31, v10
	v_lshl_add_u64 v[10:11], v[10:11], 1, v[14:15]
	global_load_dwordx4 v[112:115], v[10:11], off
	v_mad_u64_u32 v[14:15], s[0:1], v18, s31, v[16:17]
	v_readlane_b32 s0, v252, 4
	v_readlane_b32 s1, v252, 5
	v_mov_b32_e32 v127, v14
	v_lshlrev_b32_e32 v10, 4, v78
	v_lshlrev_b32_e32 v14, 2, v78
	v_and_b32_e32 v10, 0xf0, v10
	v_ashrrev_i32_e32 v15, 31, v14
	v_add_u32_e32 v16, s11, v10
	v_lshl_add_u64 v[10:11], v[14:15], 2, s[0:1]
	global_load_dwordx4 v[116:119], v[10:11], off
	v_add_u32_e32 v15, v16, v17
	v_mov_b32_e32 v128, v15
	v_lshlrev_b32_e32 v10, 2, v20
	v_ashrrev_i32_e32 v11, 31, v10
	v_lshl_add_u64 v[10:11], v[10:11], 2, s[0:1]
	global_load_dwordx4 v[120:123], v[10:11], off
	v_add_u32_e32 v15, v16, v21
	s_and_b32 s1, s2, 0xfffff800
	s_lshl_b32 s0, s7, 4
	s_and_b32 s68, s0, 0x180
	v_mov_b32_e32 v129, v15
	v_readfirstlane_b32 s22, v82
	v_and_b32_e32 v11, 63, v78
	v_lshrrev_b32_e32 v14, 3, v11
	v_and_b32_e32 v15, 7, v11
	v_xor_b32_e32 v15, v15, v14
	v_lshlrev_b32_e32 v15, 4, v15
	v_lshl_add_u32 v10, v14, 12, v15
	s_lshl_b32 s23, s22, 13
	s_add_i32 s23, s23, 0x11000
	s_cmp_lt_u32 s22, 7
	s_cselect_b32 s23, s23, 0x20400
	v_and_b32_e32 v14, 7, v80
	v_xor_b32_e32 v15, v81, v14
	v_lshlrev_b32_e32 v15, 4, v15
	v_lshl_add_u32 v12, v80, 7, v15
	v_add_u32_e32 v12, s23, v12
	v_or_b32_e32 v15, 4, v81
	v_xor_b32_e32 v15, v15, v14
	v_lshlrev_b32_e32 v15, 4, v15
	v_lshl_add_u32 v13, v80, 7, v15
	v_add_u32_e32 v13, s23, v13
	v_lshlrev_b32_e32 v14, 3, v78
	v_and_b32_e32 v84, 0x80, v14
	v_lshlrev_b32_e32 v14, 2, v78
	v_and_b32_e32 v14, 0x80, v14
	v_lshl_add_u32 v85, v82, 4, v14
	v_or_b32_e32 v72, 16, v80
	v_or_b32_e32 v14, 0x0, v80
	v_or_b32_e32 v14, v84, v14
	v_mad_u32_u24 v62, v14, s31, v85
	v_or_b32_e32 v14, 0x20, v80
	v_or_b32_e32 v14, v84, v14
	v_mad_u32_u24 v63, v14, s31, v85
	v_or_b32_e32 v14, 0x40, v80
	v_or_b32_e32 v14, v84, v14
	v_mad_u32_u24 v64, v14, s31, v85
	v_or_b32_e32 v14, 0x60, v80
	v_or_b32_e32 v14, v84, v14
	v_mad_u32_u24 v65, v14, s31, v85
	v_or_b32_e32 v14, 0x0, v72
	v_or_b32_e32 v14, v84, v14
	v_mad_u32_u24 v66, v14, s31, v85
	v_or_b32_e32 v14, 0x20, v72
	v_or_b32_e32 v14, v84, v14
	v_mad_u32_u24 v67, v14, s31, v85
	v_or_b32_e32 v14, 0x40, v72
	v_or_b32_e32 v14, v84, v14
	v_mad_u32_u24 v68, v14, s31, v85
	v_or_b32_e32 v14, 0x60, v72
	v_or_b32_e32 v14, v84, v14
	v_mad_u32_u24 v69, v14, s31, v85
	s_lshl_b32 s38, s22, 8
	s_add_i32 s38, s38, s1
	s_lshl_b32 s38, s38, 12
	s_add_u32 s38, s86, s38
	s_addc_u32 s39, s87, 0
	s_add_u32 s38, s38, s68
	s_addc_u32 s39, s39, s69
	s_add_u32 s38, s38, s95
	s_addc_u32 s39, s39, 0
	s_add_u32 s38, s38, 0x600
	s_addc_u32 s39, s39, 0
	s_add_i32 m0, s23, 0x0
	s_add_u32 s100, s38, 0x8000
	s_addc_u32 s101, s39, 0
	global_load_lds_dwordx4 v10, s[38:39]
	s_add_i32 m0, s23, 0x400
	s_add_u32 s38, s38, 0x10000
	global_load_lds_dwordx4 v10, s[100:101]
	s_addc_u32 s39, s39, 0
	s_add_i32 m0, s23, 0x800
	s_add_u32 s100, s38, 0x8000
	s_addc_u32 s101, s39, 0
	global_load_lds_dwordx4 v10, s[38:39]
	s_add_i32 m0, s23, 0xc00
	s_add_u32 s38, s38, 0x10000
	global_load_lds_dwordx4 v10, s[100:101]
	s_addc_u32 s39, s39, 0
	s_add_i32 m0, s23, 0x1000
	s_add_u32 s100, s38, 0x8000
	s_addc_u32 s101, s39, 0
	global_load_lds_dwordx4 v10, s[38:39]
	s_add_i32 m0, s23, 0x1400
	s_add_u32 s38, s38, 0x10000
	global_load_lds_dwordx4 v10, s[100:101]
	s_addc_u32 s39, s39, 0
	s_add_i32 m0, s23, 0x1800
	s_add_u32 s100, s38, 0x8000
	s_addc_u32 s101, s39, 0
	global_load_lds_dwordx4 v10, s[38:39]
	s_add_i32 m0, s23, 0x1c00
	s_add_u32 s38, s38, 0x10000
	global_load_lds_dwordx4 v10, s[100:101]
	s_addc_u32 s39, s39, 0
	s_waitcnt vmcnt(6)
	ds_read_b128 v[14:17], v12
	ds_read_b128 v[18:21], v13
	s_waitcnt lgkmcnt(0)
	s_add_i32 m0, s23, 0x0
	s_add_u32 s100, s38, 0x8000
	s_addc_u32 s101, s39, 0
	global_load_lds_dwordx4 v10, s[38:39]
	s_add_i32 m0, s23, 0x400
	s_add_u32 s38, s38, 0x10000
	global_load_lds_dwordx4 v10, s[100:101]
	s_addc_u32 s39, s39, 0
	v_mfma_f32_16x16x32_bf16 v[30:33], v[6:9], v[14:17], 0
	v_mfma_f32_16x16x32_bf16 v[30:33], v[2:5], v[18:21], v[30:33]
	s_waitcnt vmcnt(6)
	ds_read_b128 v[22:25], v12 offset:2048
	ds_read_b128 v[26:29], v13 offset:2048
	s_waitcnt lgkmcnt(0)
	s_add_i32 m0, s23, 0x800
	s_add_u32 s100, s38, 0x8000
	s_addc_u32 s101, s39, 0
	global_load_lds_dwordx4 v10, s[38:39]
	s_add_i32 m0, s23, 0xc00
	s_add_u32 s38, s38, 0x10000
	global_load_lds_dwordx4 v10, s[100:101]
	s_addc_u32 s39, s39, 0
	v_mfma_f32_16x16x32_bf16 v[34:37], v[6:9], v[22:25], 0
	v_mfma_f32_16x16x32_bf16 v[34:37], v[2:5], v[26:29], v[34:37]
	s_waitcnt vmcnt(6)
	ds_read_b128 v[14:17], v12 offset:4096
	ds_read_b128 v[18:21], v13 offset:4096
	s_waitcnt lgkmcnt(0)
	s_add_i32 m0, s23, 0x1000
	s_add_u32 s100, s38, 0x8000
	s_addc_u32 s101, s39, 0
	global_load_lds_dwordx4 v10, s[38:39]
	s_add_i32 m0, s23, 0x1400
	s_add_u32 s38, s38, 0x10000
	global_load_lds_dwordx4 v10, s[100:101]
	s_addc_u32 s39, s39, 0
	v_mfma_f32_16x16x32_bf16 v[38:41], v[6:9], v[14:17], 0
	v_mfma_f32_16x16x32_bf16 v[38:41], v[2:5], v[18:21], v[38:41]
	s_waitcnt vmcnt(6)
	ds_read_b128 v[22:25], v12 offset:6144
	ds_read_b128 v[26:29], v13 offset:6144
	s_waitcnt lgkmcnt(0)
	s_add_i32 m0, s23, 0x1800
	s_add_u32 s100, s38, 0x8000
	s_addc_u32 s101, s39, 0
	global_load_lds_dwordx4 v10, s[38:39]
	s_add_i32 m0, s23, 0x1c00
	s_add_u32 s38, s38, 0x10000
	global_load_lds_dwordx4 v10, s[100:101]
	s_addc_u32 s39, s39, 0
	v_mfma_f32_16x16x32_bf16 v[42:45], v[6:9], v[22:25], 0
	v_mfma_f32_16x16x32_bf16 v[42:45], v[2:5], v[26:29], v[42:45]
	s_waitcnt vmcnt(6)
	ds_read_b128 v[14:17], v12
	ds_read_b128 v[18:21], v13
	s_waitcnt lgkmcnt(0)
	s_add_i32 m0, s23, 0x0
	s_add_u32 s100, s38, 0x8000
	s_addc_u32 s101, s39, 0
	global_load_lds_dwordx4 v10, s[38:39]
	s_add_i32 m0, s23, 0x400
	s_add_u32 s38, s38, 0x10000
	global_load_lds_dwordx4 v10, s[100:101]
	s_addc_u32 s39, s39, 0
	v_mfma_f32_16x16x32_bf16 v[46:49], v[6:9], v[14:17], 0
	v_mfma_f32_16x16x32_bf16 v[46:49], v[2:5], v[18:21], v[46:49]
	s_waitcnt vmcnt(6)
	ds_read_b128 v[22:25], v12 offset:2048
	ds_read_b128 v[26:29], v13 offset:2048
	s_waitcnt lgkmcnt(0)
	s_add_i32 m0, s23, 0x800
	s_add_u32 s100, s38, 0x8000
	s_addc_u32 s101, s39, 0
	global_load_lds_dwordx4 v10, s[38:39]
	s_add_i32 m0, s23, 0xc00
	s_add_u32 s38, s38, 0x10000
	global_load_lds_dwordx4 v10, s[100:101]
	s_addc_u32 s39, s39, 0
	v_mfma_f32_16x16x32_bf16 v[50:53], v[6:9], v[22:25], 0
	v_mfma_f32_16x16x32_bf16 v[50:53], v[2:5], v[26:29], v[50:53]
	s_waitcnt vmcnt(6)
	ds_read_b128 v[14:17], v12 offset:4096
	ds_read_b128 v[18:21], v13 offset:4096
	s_waitcnt lgkmcnt(0)
	s_add_i32 m0, s23, 0x1000
	s_add_u32 s100, s38, 0x8000
	s_addc_u32 s101, s39, 0
	global_load_lds_dwordx4 v10, s[38:39]
	s_add_i32 m0, s23, 0x1400
	s_add_u32 s38, s38, 0x10000
	global_load_lds_dwordx4 v10, s[100:101]
	s_addc_u32 s39, s39, 0
	v_mfma_f32_16x16x32_bf16 v[54:57], v[6:9], v[14:17], 0
	v_mfma_f32_16x16x32_bf16 v[54:57], v[2:5], v[18:21], v[54:57]
	s_waitcnt vmcnt(6)
	ds_read_b128 v[22:25], v12 offset:6144
	ds_read_b128 v[26:29], v13 offset:6144
	s_waitcnt lgkmcnt(0)
	s_add_i32 m0, s23, 0x1800
	s_add_u32 s100, s38, 0x8000
	s_addc_u32 s101, s39, 0
	global_load_lds_dwordx4 v10, s[38:39]
	s_add_i32 m0, s23, 0x1c00
	s_add_u32 s38, s38, 0x10000
	global_load_lds_dwordx4 v10, s[100:101]
	s_addc_u32 s39, s39, 0
	v_mfma_f32_16x16x32_bf16 v[58:61], v[6:9], v[22:25], 0
	v_mfma_f32_16x16x32_bf16 v[58:61], v[2:5], v[26:29], v[58:61]
	s_nop 7
	s_nop 3
	v_cvt_pk_bf16_f32 v86, v30, v38
	v_cvt_pk_bf16_f32 v87, v46, v54
	ds_write_b64 v62, v[86:87]
	v_cvt_pk_bf16_f32 v88, v31, v39
	v_cvt_pk_bf16_f32 v89, v47, v55
	ds_write_b64 v63, v[88:89]
	v_cvt_pk_bf16_f32 v86, v32, v40
	v_cvt_pk_bf16_f32 v87, v48, v56
	ds_write_b64 v64, v[86:87]
	v_cvt_pk_bf16_f32 v88, v33, v41
	v_cvt_pk_bf16_f32 v89, v49, v57
	ds_write_b64 v65, v[88:89]
	v_cvt_pk_bf16_f32 v86, v34, v42
	v_cvt_pk_bf16_f32 v87, v50, v58
	ds_write_b64 v66, v[86:87]
	v_cvt_pk_bf16_f32 v88, v35, v43
	v_cvt_pk_bf16_f32 v89, v51, v59
	ds_write_b64 v67, v[88:89]
	v_cvt_pk_bf16_f32 v86, v36, v44
	v_cvt_pk_bf16_f32 v87, v52, v60
	ds_write_b64 v68, v[86:87]
	v_cvt_pk_bf16_f32 v88, v37, v45
	v_cvt_pk_bf16_f32 v89, v53, v61
	ds_write_b64 v69, v[88:89]
	s_waitcnt vmcnt(6)
	ds_read_b128 v[14:17], v12
	ds_read_b128 v[18:21], v13
	s_waitcnt lgkmcnt(0)
	s_add_i32 m0, s23, 0x0
	s_add_u32 s100, s38, 0x8000
	s_addc_u32 s101, s39, 0
	global_load_lds_dwordx4 v10, s[38:39]
	s_add_i32 m0, s23, 0x400
	s_add_u32 s38, s38, 0x10000
	global_load_lds_dwordx4 v10, s[100:101]
	s_addc_u32 s39, s39, 0
	v_mfma_f32_16x16x32_bf16 v[30:33], v[6:9], v[14:17], 0
	v_mfma_f32_16x16x32_bf16 v[30:33], v[2:5], v[18:21], v[30:33]
	s_waitcnt vmcnt(6)
	ds_read_b128 v[22:25], v12 offset:2048
	ds_read_b128 v[26:29], v13 offset:2048
	s_waitcnt lgkmcnt(0)
	s_add_i32 m0, s23, 0x800
	s_add_u32 s100, s38, 0x8000
	s_addc_u32 s101, s39, 0
	global_load_lds_dwordx4 v10, s[38:39]
	s_add_i32 m0, s23, 0xc00
	s_add_u32 s38, s38, 0x10000
	global_load_lds_dwordx4 v10, s[100:101]
	s_addc_u32 s39, s39, 0
	v_mfma_f32_16x16x32_bf16 v[34:37], v[6:9], v[22:25], 0
	v_mfma_f32_16x16x32_bf16 v[34:37], v[2:5], v[26:29], v[34:37]
	s_waitcnt vmcnt(6)
	ds_read_b128 v[14:17], v12 offset:4096
	ds_read_b128 v[18:21], v13 offset:4096
	s_waitcnt lgkmcnt(0)
	s_add_i32 m0, s23, 0x1000
	s_add_u32 s100, s38, 0x8000
	s_addc_u32 s101, s39, 0
	global_load_lds_dwordx4 v10, s[38:39]
	s_add_i32 m0, s23, 0x1400
	s_add_u32 s38, s38, 0x10000
	global_load_lds_dwordx4 v10, s[100:101]
	s_addc_u32 s39, s39, 0
	v_mfma_f32_16x16x32_bf16 v[38:41], v[6:9], v[14:17], 0
	v_mfma_f32_16x16x32_bf16 v[38:41], v[2:5], v[18:21], v[38:41]
	s_waitcnt vmcnt(6)
	ds_read_b128 v[22:25], v12 offset:6144
	ds_read_b128 v[26:29], v13 offset:6144
	s_waitcnt lgkmcnt(0)
	s_add_i32 m0, s23, 0x1800
	s_add_u32 s100, s38, 0x8000
	s_addc_u32 s101, s39, 0
	global_load_lds_dwordx4 v10, s[38:39]
	s_add_i32 m0, s23, 0x1c00
	s_add_u32 s38, s38, 0x10000
	global_load_lds_dwordx4 v10, s[100:101]
	s_addc_u32 s39, s39, 0
	v_mfma_f32_16x16x32_bf16 v[42:45], v[6:9], v[22:25], 0
	v_mfma_f32_16x16x32_bf16 v[42:45], v[2:5], v[26:29], v[42:45]
	s_waitcnt vmcnt(6)
	ds_read_b128 v[14:17], v12
	ds_read_b128 v[18:21], v13
	s_waitcnt lgkmcnt(0)
	v_mfma_f32_16x16x32_bf16 v[46:49], v[6:9], v[14:17], 0
	v_mfma_f32_16x16x32_bf16 v[46:49], v[2:5], v[18:21], v[46:49]
	s_waitcnt vmcnt(4)
	ds_read_b128 v[22:25], v12 offset:2048
	ds_read_b128 v[26:29], v13 offset:2048
	s_waitcnt lgkmcnt(0)
	v_mfma_f32_16x16x32_bf16 v[50:53], v[6:9], v[22:25], 0
	v_mfma_f32_16x16x32_bf16 v[50:53], v[2:5], v[26:29], v[50:53]
	s_waitcnt vmcnt(2)
	ds_read_b128 v[14:17], v12 offset:4096
	ds_read_b128 v[18:21], v13 offset:4096
	s_waitcnt lgkmcnt(0)
	v_mfma_f32_16x16x32_bf16 v[54:57], v[6:9], v[14:17], 0
	v_mfma_f32_16x16x32_bf16 v[54:57], v[2:5], v[18:21], v[54:57]
	s_waitcnt vmcnt(0)
	ds_read_b128 v[22:25], v12 offset:6144
	ds_read_b128 v[26:29], v13 offset:6144
	s_waitcnt lgkmcnt(0)
	v_mfma_f32_16x16x32_bf16 v[58:61], v[6:9], v[22:25], 0
	v_mfma_f32_16x16x32_bf16 v[58:61], v[2:5], v[26:29], v[58:61]
	s_nop 7
	s_nop 3
	v_cvt_pk_bf16_f32 v86, v30, v38
	v_cvt_pk_bf16_f32 v87, v46, v54
	ds_write_b64 v62, v[86:87] offset:8
	v_cvt_pk_bf16_f32 v88, v31, v39
	v_cvt_pk_bf16_f32 v89, v47, v55
	ds_write_b64 v63, v[88:89] offset:8
	v_cvt_pk_bf16_f32 v86, v32, v40
	v_cvt_pk_bf16_f32 v87, v48, v56
	ds_write_b64 v64, v[86:87] offset:8
	v_cvt_pk_bf16_f32 v88, v33, v41
	v_cvt_pk_bf16_f32 v89, v49, v57
	ds_write_b64 v65, v[88:89] offset:8
	v_cvt_pk_bf16_f32 v86, v34, v42
	v_cvt_pk_bf16_f32 v87, v50, v58
	ds_write_b64 v66, v[86:87] offset:8
	v_cvt_pk_bf16_f32 v88, v35, v43
	v_cvt_pk_bf16_f32 v89, v51, v59
	ds_write_b64 v67, v[88:89] offset:8
	v_cvt_pk_bf16_f32 v86, v36, v44
	v_cvt_pk_bf16_f32 v87, v52, v60
	ds_write_b64 v68, v[86:87] offset:8
	v_cvt_pk_bf16_f32 v88, v37, v45
	v_cvt_pk_bf16_f32 v89, v53, v61
	ds_write_b64 v69, v[88:89] offset:8
	s_waitcnt lgkmcnt(0)
	s_barrier
	ds_write_b128 v124, v[100:103]
	ds_write_b128 v125, v[104:107]
	ds_write_b128 v126, v[108:111]
	ds_write_b128 v127, v[112:115]
	ds_write_b128 v128, v[116:119]
	ds_write_b128 v129, v[120:123]
	v_lshl_or_b32 v18, v82, 5, v80
	v_mul_lo_u32 v18, v18, s31
	v_mov_b32_e32 v36, 0x1100
	s_nop 0
	v_mov_b32_e32 v44, 0x2200
	v_mov_b32_e32 v53, 0x3300
	v_lshl_add_u64 v[2:3], s[8:9], 0, v[74:75]
	v_add3_u32 v31, 0, v18, v74
	v_add_u32_e32 v52, s10, v74
	v_mad_u32_u24 v75, v80, s31, v36
	v_mad_u32_u24 v74, v80, s31, v44
	v_mad_u32_u24 v73, v80, s31, v53
	v_lshl_add_u64 v[2:3], v[2:3], 0, v[98:99]
	v_mad_u32_u24 v30, v80, s31, v52
	v_add_u32_e32 v76, v52, v75
	v_add_u32_e32 v77, v52, v74
	v_add_u32_e32 v96, v52, v73
	global_load_dwordx4 v[10:13], v[2:3], off
	global_load_dwordx4 v[6:9], v[2:3], off offset:64
	global_load_dwordx4 v[14:17], v[2:3], off offset:2048
	s_nop 0
	global_load_dwordx4 v[2:5], v[2:3], off offset:2112
	s_waitcnt lgkmcnt(0)
	s_barrier
	ds_read_b128 v[18:21], v31
	ds_read_b128 v[22:25], v31 offset:4352
	ds_read_b128 v[26:29], v30
	ds_read_b128 v[60:63], v30 offset:17408
	ds_read_b128 v[36:39], v76
	ds_read_b128 v[100:103], v30 offset:30464
	ds_read_b128 v[44:47], v77
	ds_read_b128 v[52:55], v96
	ds_read_b128 v[68:71], v30 offset:21760
	ds_read_b128 v[88:91], v30 offset:26112
	s_waitcnt lgkmcnt(7)
	v_mfma_f32_16x16x32_bf16 v[32:35], v[18:21], v[26:29], 0
	s_movk_i32 s10, 0x90
	v_bfe_u32 v98, v78, 1, 3
	v_mfma_f32_16x16x32_bf16 v[26:29], v[22:25], v[26:29], 0
	s_waitcnt lgkmcnt(5)
	v_mfma_f32_16x16x32_bf16 v[40:43], v[18:21], v[36:39], 0
	v_mfma_f32_16x16x32_bf16 v[36:39], v[22:25], v[36:39], 0
	s_waitcnt lgkmcnt(3)
	v_mfma_f32_16x16x32_bf16 v[48:51], v[18:21], v[44:47], 0
	v_mfma_f32_16x16x32_bf16 v[44:47], v[22:25], v[44:47], 0
	s_waitcnt lgkmcnt(2)
	v_mfma_f32_16x16x32_bf16 v[56:59], v[18:21], v[52:55], 0
	v_mfma_f32_16x16x32_bf16 v[52:55], v[22:25], v[52:55], 0
	v_mfma_f32_16x16x32_bf16 v[64:67], v[18:21], v[60:63], 0
	v_mfma_f32_16x16x32_bf16 v[60:63], v[22:25], v[60:63], 0
	s_waitcnt lgkmcnt(1)
	v_mfma_f32_16x16x32_bf16 v[84:87], v[18:21], v[68:71], 0
	v_mfma_f32_16x16x32_bf16 v[68:71], v[22:25], v[68:71], 0
	s_waitcnt lgkmcnt(0)
	v_mfma_f32_16x16x32_bf16 v[92:95], v[18:21], v[88:91], 0
	v_mfma_f32_16x16x32_bf16 v[88:91], v[22:25], v[88:91], 0
	v_mfma_f32_16x16x32_bf16 v[18:21], v[18:21], v[100:103], 0
	v_mfma_f32_16x16x32_bf16 v[22:25], v[22:25], v[100:103], 0
	ds_read_b128 v[100:103], v31 offset:64
	ds_read_b128 v[104:107], v31 offset:4416
	ds_read_b128 v[108:111], v30 offset:64
	s_waitcnt lgkmcnt(0)
	v_mfma_f32_16x16x32_bf16 v[32:35], v[100:103], v[108:111], v[32:35]
	v_mfma_f32_16x16x32_bf16 v[26:29], v[104:107], v[108:111], v[26:29]
	ds_read_b128 v[108:111], v76 offset:64
	s_waitcnt lgkmcnt(0)
	v_mfma_f32_16x16x32_bf16 v[40:43], v[100:103], v[108:111], v[40:43]
	v_mfma_f32_16x16x32_bf16 v[36:39], v[104:107], v[108:111], v[36:39]
	ds_read_b128 v[108:111], v77 offset:64
	s_waitcnt lgkmcnt(0)
	v_mfma_f32_16x16x32_bf16 v[48:51], v[100:103], v[108:111], v[48:51]
	v_mfma_f32_16x16x32_bf16 v[44:47], v[104:107], v[108:111], v[44:47]
	ds_read_b128 v[108:111], v96 offset:64
	s_waitcnt lgkmcnt(0)
	v_mfma_f32_16x16x32_bf16 v[56:59], v[100:103], v[108:111], v[56:59]
	v_mfma_f32_16x16x32_bf16 v[52:55], v[104:107], v[108:111], v[52:55]
	ds_read_b128 v[108:111], v30 offset:17472
	s_waitcnt lgkmcnt(0)
	v_mfma_f32_16x16x32_bf16 v[64:67], v[100:103], v[108:111], v[64:67]
	v_mfma_f32_16x16x32_bf16 v[60:63], v[104:107], v[108:111], v[60:63]
	ds_read_b128 v[108:111], v30 offset:21824
	s_waitcnt lgkmcnt(0)
	v_mfma_f32_16x16x32_bf16 v[84:87], v[100:103], v[108:111], v[84:87]
	v_mfma_f32_16x16x32_bf16 v[68:71], v[104:107], v[108:111], v[68:71]
	ds_read_b128 v[108:111], v30 offset:26176
	s_waitcnt lgkmcnt(0)
	v_mfma_f32_16x16x32_bf16 v[92:95], v[100:103], v[108:111], v[92:95]
	v_mfma_f32_16x16x32_bf16 v[88:91], v[104:107], v[108:111], v[88:91]
	ds_read_b128 v[108:111], v30 offset:30528
	s_waitcnt lgkmcnt(0)
	v_mfma_f32_16x16x32_bf16 v[18:21], v[100:103], v[108:111], v[18:21]
	v_mfma_f32_16x16x32_bf16 v[22:25], v[104:107], v[108:111], v[22:25]
	ds_read_b128 v[100:103], v31 offset:128
	ds_read_b128 v[104:107], v31 offset:4480
	ds_read_b128 v[108:111], v30 offset:128
	s_waitcnt lgkmcnt(0)
	v_mfma_f32_16x16x32_bf16 v[32:35], v[100:103], v[108:111], v[32:35]
	v_mfma_f32_16x16x32_bf16 v[26:29], v[104:107], v[108:111], v[26:29]
	ds_read_b128 v[108:111], v76 offset:128
	s_waitcnt lgkmcnt(0)
	v_mfma_f32_16x16x32_bf16 v[40:43], v[100:103], v[108:111], v[40:43]
	v_mfma_f32_16x16x32_bf16 v[36:39], v[104:107], v[108:111], v[36:39]
	ds_read_b128 v[108:111], v77 offset:128
	s_waitcnt lgkmcnt(0)
	v_mfma_f32_16x16x32_bf16 v[112:115], v[100:103], v[108:111], v[48:51]
	v_mfma_f32_16x16x32_bf16 v[46:49], v[104:107], v[108:111], v[44:47]
	ds_read_b128 v[108:111], v96 offset:128
	s_waitcnt lgkmcnt(0)
	v_mfma_f32_16x16x32_bf16 v[56:59], v[100:103], v[108:111], v[56:59]
	v_mfma_f32_16x16x32_bf16 v[108:111], v[104:107], v[108:111], v[52:55]
	s_nop 2
	ds_read_b128 v[50:53], v30 offset:17536
	s_waitcnt lgkmcnt(0)
	v_mfma_f32_16x16x32_bf16 v[116:119], v[100:103], v[50:53], v[64:67]
	v_mfma_f32_16x16x32_bf16 v[120:123], v[104:107], v[50:53], v[60:63]
	ds_read_b128 v[50:53], v30 offset:21888
	s_waitcnt lgkmcnt(0)
	v_mfma_f32_16x16x32_bf16 v[84:87], v[100:103], v[50:53], v[84:87]
	v_mfma_f32_16x16x32_bf16 v[124:127], v[104:107], v[50:53], v[68:71]
	ds_read_b128 v[50:53], v30 offset:26240
	s_waitcnt lgkmcnt(0)
	v_mfma_f32_16x16x32_bf16 v[92:95], v[100:103], v[50:53], v[92:95]
	v_mfma_f32_16x16x32_bf16 v[88:91], v[104:107], v[50:53], v[88:91]
	ds_read_b128 v[50:53], v30 offset:30592
	s_waitcnt lgkmcnt(0)
	v_mfma_f32_16x16x32_bf16 v[100:103], v[100:103], v[50:53], v[18:21]
	ds_read_b128 v[128:131], v31 offset:192
	ds_read_b128 v[132:135], v31 offset:4544
	s_nop 0
	ds_read_b128 v[18:21], v30 offset:192
	s_waitcnt lgkmcnt(0)
	v_mfma_f32_16x16x32_bf16 v[136:139], v[128:131], v[18:21], v[32:35]
	v_mfma_f32_16x16x32_bf16 v[62:65], v[132:135], v[18:21], v[26:29]
	ds_read_b128 v[18:21], v76 offset:192
	v_bfe_u32 v76, v83, 1, 1
	v_mfma_f32_16x16x32_bf16 v[104:107], v[104:107], v[50:53], v[22:25]
	s_waitcnt lgkmcnt(0)
	v_mfma_f32_16x16x32_bf16 v[50:53], v[128:131], v[18:21], v[40:43]
	v_mfma_f32_16x16x32_bf16 v[42:45], v[132:135], v[18:21], v[36:39]
	ds_read_b128 v[18:21], v77 offset:192
	s_nop 1
	ds_read_b128 v[38:41], v30 offset:17600
	s_waitcnt lgkmcnt(1)
	v_mfma_f32_16x16x32_bf16 v[34:37], v[128:131], v[18:21], v[112:115]
	v_lshl_add_u32 v77, v81, 5, s11
	v_mad_u32_u24 v83, v80, s31, v77
	v_add_u32_e32 v75, v77, v75
	v_mfma_f32_16x16x32_bf16 v[26:29], v[132:135], v[18:21], v[46:49]
	ds_read_b128 v[18:21], v96 offset:192
	s_waitcnt lgkmcnt(0)
	v_mfma_f32_16x16x32_bf16 v[22:25], v[128:131], v[18:21], v[56:59]
	v_mfma_f32_16x16x32_bf16 v[18:21], v[132:135], v[18:21], v[108:111]
	v_mfma_f32_16x16x32_bf16 v[108:111], v[128:131], v[38:41], v[116:119]
	v_mfma_f32_16x16x32_bf16 v[112:115], v[132:135], v[38:41], v[120:123]
	ds_read_b128 v[38:41], v30 offset:21952
	s_waitcnt lgkmcnt(0)
	v_mfma_f32_16x16x32_bf16 v[66:69], v[128:131], v[38:41], v[84:87]
	v_mfma_f32_16x16x32_bf16 v[58:61], v[132:135], v[38:41], v[124:127]
	ds_read_b128 v[38:41], v30 offset:26304
	ds_read_b128 v[30:33], v30 offset:30656
	s_waitcnt lgkmcnt(0)
	v_mfma_f32_16x16x32_bf16 v[46:49], v[132:135], v[38:41], v[88:91]
	s_barrier
	ds_read_b128 v[84:87], v83
	s_nop 0
	ds_read_b128 v[88:91], v83 offset:16
	v_mfma_f32_16x16x32_bf16 v[54:57], v[128:131], v[38:41], v[92:95]
	s_waitcnt lgkmcnt(0)
	v_mov_b32_e32 v97, v90
	s_nop 0
	v_lshrrev_b32_e32 v93, 1, v78
	v_mov_b32_e32 v95, v86
	v_mov_b32_e32 v86, v85
	v_mov_b32_e32 v90, v89
	v_and_b32_e32 v70, 8, v93
	v_mov_b32_e32 v94, v84
	v_pk_mul_f32 v[84:85], v[108:109], v[86:87]
	v_mov_b32_e32 v96, v88
	v_pk_mul_f32 v[88:89], v[110:111], v[90:91]
	v_add_u32_e32 v92, 0, v70
	v_lshl_add_u32 v70, v80, 3, v82
	v_pk_fma_f32 v[84:85], v[136:137], v[94:95], v[84:85] neg_lo:[0,0,1] neg_hi:[0,0,1]
	v_pk_fma_f32 v[88:89], v[138:139], v[96:97], v[88:89] neg_lo:[0,0,1] neg_hi:[0,0,1]
	v_mad_u64_u32 v[70:71], s[8:9], v70, s10, v[92:93]
	v_cvt_pk_bf16_f32 v84, v84, v85
	v_cvt_pk_bf16_f32 v85, v88, v89
	v_pk_mul_f32 v[88:89], v[108:109], v[94:95]
	v_bitop3_b32 v71, v76, v93, 7 bitop3:0x78
	v_pk_fma_f32 v[86:87], v[136:137], v[86:87], v[88:89]
	v_pk_mul_f32 v[88:89], v[110:111], v[96:97]
	v_lshlrev_b32_e32 v71, 4, v71
	v_pk_fma_f32 v[88:89], v[138:139], v[90:91], v[88:89]
	v_cvt_pk_bf16_f32 v86, v86, v87
	v_cvt_pk_bf16_f32 v87, v88, v89
	v_add_u32_e32 v88, v70, v71
	ds_write_b64 v88, v[84:85]
	v_bitop3_b32 v84, v76, v98, 4 bitop3:0x36
	v_mfma_f32_16x16x32_bf16 v[38:41], v[128:131], v[30:33], v[100:103]
	s_nop 2
	v_lshlrev_b32_e32 v100, 4, v84
	v_add_u32_e32 v84, v70, v100
	ds_write_b64 v84, v[86:87]
	ds_read_b128 v[84:87], v83 offset:128
	ds_read_b128 v[88:91], v83 offset:144
	v_mfma_f32_16x16x32_bf16 v[30:33], v[132:135], v[30:33], v[104:107]
	s_waitcnt lgkmcnt(1)
	v_mov_b32_e32 v95, v86
	v_mov_b32_e32 v86, v85
	s_waitcnt lgkmcnt(0)
	v_mov_b32_e32 v97, v90
	v_mov_b32_e32 v90, v89
	v_mov_b32_e32 v94, v84
	v_pk_mul_f32 v[84:85], v[112:113], v[86:87]
	v_mov_b32_e32 v96, v88
	v_pk_mul_f32 v[88:89], v[114:115], v[90:91]
	v_pk_fma_f32 v[84:85], v[62:63], v[94:95], v[84:85] neg_lo:[0,0,1] neg_hi:[0,0,1]
	v_pk_fma_f32 v[88:89], v[64:65], v[96:97], v[88:89] neg_lo:[0,0,1] neg_hi:[0,0,1]
	v_cvt_pk_bf16_f32 v84, v84, v85
	v_cvt_pk_bf16_f32 v85, v88, v89
	v_pk_mul_f32 v[88:89], v[112:113], v[94:95]
	s_nop 0
	v_pk_fma_f32 v[62:63], v[62:63], v[86:87], v[88:89]
	v_pk_mul_f32 v[86:87], v[114:115], v[96:97]
	v_cvt_pk_bf16_f32 v62, v62, v63
	v_pk_fma_f32 v[64:65], v[64:65], v[90:91], v[86:87]
	s_nop 0
	v_cvt_pk_bf16_f32 v63, v64, v65
	v_bitop3_b32 v64, v76, v98, 2 bitop3:0x36
	v_lshlrev_b32_e32 v83, 4, v64
	v_add_u32_e32 v64, v70, v83
	ds_write_b64 v64, v[84:85]
	v_bitop3_b32 v64, v76, v98, 6 bitop3:0x36
	v_lshlrev_b32_e32 v94, 4, v64
	v_add_u32_e32 v64, v70, v94
	ds_write_b64 v64, v[62:63]
	v_lshl_add_u32 v62, v72, 3, v82
	v_mad_u64_u32 v[88:89], s[8:9], v62, s10, v[92:93]
	ds_read_b128 v[62:65], v75
	ds_read_b128 v[84:87], v75 offset:16
	s_waitcnt lgkmcnt(1)
	v_mov_b32_e32 v90, v62
	v_mov_b32_e32 v91, v64
	v_mov_b32_e32 v64, v63
	v_pk_mul_f32 v[62:63], v[66:67], v[64:65]
	s_waitcnt lgkmcnt(0)
	v_mov_b32_e32 v92, v84
	v_mov_b32_e32 v93, v86
	v_mov_b32_e32 v86, v85
	v_pk_mul_f32 v[66:67], v[66:67], v[90:91]
	v_pk_fma_f32 v[62:63], v[50:51], v[90:91], v[62:63] neg_lo:[0,0,1] neg_hi:[0,0,1]
	v_pk_mul_f32 v[84:85], v[68:69], v[86:87]
	v_pk_fma_f32 v[50:51], v[50:51], v[64:65], v[66:67]
	v_pk_mul_f32 v[64:65], v[68:69], v[92:93]
	v_pk_fma_f32 v[84:85], v[52:53], v[92:93], v[84:85] neg_lo:[0,0,1] neg_hi:[0,0,1]
	v_pk_fma_f32 v[52:53], v[52:53], v[86:87], v[64:65]
	v_cvt_pk_bf16_f32 v62, v62, v63
	v_cvt_pk_bf16_f32 v63, v84, v85
	v_cvt_pk_bf16_f32 v50, v50, v51
	v_cvt_pk_bf16_f32 v51, v52, v53
	v_add_u32_e32 v52, v88, v71
	ds_write_b64 v52, v[62:63]
	v_add_u32_e32 v52, v88, v100
	ds_write_b64 v52, v[50:51]
	ds_read_b128 v[50:53], v75 offset:128
	ds_read_b128 v[62:65], v75 offset:144
	s_waitcnt lgkmcnt(1)
	v_mov_b32_e32 v66, v50
	v_mov_b32_e32 v67, v52
	v_mov_b32_e32 v52, v51
	v_pk_mul_f32 v[50:51], v[58:59], v[52:53]
	s_waitcnt lgkmcnt(0)
	v_mov_b32_e32 v68, v62
	v_mov_b32_e32 v69, v64
	v_mov_b32_e32 v64, v63
	v_pk_mul_f32 v[58:59], v[58:59], v[66:67]
	v_pk_fma_f32 v[50:51], v[42:43], v[66:67], v[50:51] neg_lo:[0,0,1] neg_hi:[0,0,1]
	v_pk_mul_f32 v[62:63], v[60:61], v[64:65]
	v_pk_fma_f32 v[42:43], v[42:43], v[52:53], v[58:59]
	v_pk_mul_f32 v[52:53], v[60:61], v[68:69]
	v_pk_fma_f32 v[62:63], v[44:45], v[68:69], v[62:63] neg_lo:[0,0,1] neg_hi:[0,0,1]
	v_pk_fma_f32 v[44:45], v[44:45], v[64:65], v[52:53]
	v_cvt_pk_bf16_f32 v50, v50, v51
	v_cvt_pk_bf16_f32 v51, v62, v63
	v_cvt_pk_bf16_f32 v42, v42, v43
	v_cvt_pk_bf16_f32 v43, v44, v45
	v_add_u32_e32 v44, v88, v83
	ds_write_b64 v44, v[50:51]
	v_add_u32_e32 v44, v88, v94
	ds_write_b64 v44, v[42:43]
	v_add_u32_e32 v62, v77, v74
	ds_read_b128 v[42:45], v62
	ds_read_b128 v[50:53], v62 offset:16
	v_add_u32_e32 v63, 0x9000, v70
	s_waitcnt lgkmcnt(1)
	v_mov_b32_e32 v59, v44
	v_mov_b32_e32 v44, v43
	s_waitcnt lgkmcnt(0)
	v_mov_b32_e32 v61, v52
	v_mov_b32_e32 v52, v51
	v_mov_b32_e32 v58, v42
	v_pk_mul_f32 v[42:43], v[54:55], v[44:45]
	v_mov_b32_e32 v60, v50
	v_pk_mul_f32 v[50:51], v[56:57], v[52:53]
	v_pk_fma_f32 v[42:43], v[34:35], v[58:59], v[42:43] neg_lo:[0,0,1] neg_hi:[0,0,1]
	v_pk_fma_f32 v[50:51], v[36:37], v[60:61], v[50:51] neg_lo:[0,0,1] neg_hi:[0,0,1]
	v_cvt_pk_bf16_f32 v42, v42, v43
	v_cvt_pk_bf16_f32 v43, v50, v51
	v_pk_mul_f32 v[50:51], v[54:55], v[58:59]
	s_nop 0
	v_pk_fma_f32 v[34:35], v[34:35], v[44:45], v[50:51]
	v_pk_mul_f32 v[44:45], v[56:57], v[60:61]
	v_cvt_pk_bf16_f32 v34, v34, v35
	v_pk_fma_f32 v[36:37], v[36:37], v[52:53], v[44:45]
	s_nop 0
	v_cvt_pk_bf16_f32 v35, v36, v37
	v_add_u32_e32 v36, v63, v71
	ds_write_b64 v36, v[42:43]
	v_add_u32_e32 v36, v63, v100
	ds_write_b64 v36, v[34:35]
	ds_read_b128 v[34:37], v62 offset:128
	ds_read_b128 v[42:45], v62 offset:144
	s_waitcnt lgkmcnt(1)
	v_mov_b32_e32 v51, v36
	v_mov_b32_e32 v36, v35
	s_waitcnt lgkmcnt(0)
	v_mov_b32_e32 v53, v44
	v_mov_b32_e32 v44, v43
	v_mov_b32_e32 v50, v34
	v_pk_mul_f32 v[34:35], v[46:47], v[36:37]
	v_mov_b32_e32 v52, v42
	v_pk_mul_f32 v[42:43], v[48:49], v[44:45]
	v_pk_fma_f32 v[34:35], v[26:27], v[50:51], v[34:35] neg_lo:[0,0,1] neg_hi:[0,0,1]
	v_pk_fma_f32 v[42:43], v[28:29], v[52:53], v[42:43] neg_lo:[0,0,1] neg_hi:[0,0,1]
	v_cvt_pk_bf16_f32 v34, v34, v35
	v_cvt_pk_bf16_f32 v35, v42, v43
	v_pk_mul_f32 v[42:43], v[46:47], v[50:51]
	v_add_u32_e32 v46, v77, v73
	v_pk_fma_f32 v[26:27], v[26:27], v[36:37], v[42:43]
	v_pk_mul_f32 v[36:37], v[48:49], v[52:53]
	v_cvt_pk_bf16_f32 v26, v26, v27
	v_pk_fma_f32 v[28:29], v[28:29], v[44:45], v[36:37]
	v_add_u32_e32 v47, 0xd800, v70
	v_cvt_pk_bf16_f32 v27, v28, v29
	v_add_u32_e32 v28, v63, v83
	ds_write_b64 v28, v[34:35]
	v_add_u32_e32 v28, v63, v94
	ds_write_b64 v28, v[26:27]
	ds_read_b128 v[26:29], v46
	ds_read_b128 v[34:37], v46 offset:16
	s_waitcnt lgkmcnt(1)
	v_mov_b32_e32 v43, v28
	v_mov_b32_e32 v28, v27
	s_waitcnt lgkmcnt(0)
	v_mov_b32_e32 v45, v36
	v_mov_b32_e32 v36, v35
	v_mov_b32_e32 v42, v26
	v_pk_mul_f32 v[26:27], v[38:39], v[28:29]
	v_mov_b32_e32 v44, v34
	v_pk_mul_f32 v[34:35], v[40:41], v[36:37]
	v_pk_fma_f32 v[26:27], v[22:23], v[42:43], v[26:27] neg_lo:[0,0,1] neg_hi:[0,0,1]
	v_pk_fma_f32 v[34:35], v[24:25], v[44:45], v[34:35] neg_lo:[0,0,1] neg_hi:[0,0,1]
	v_cvt_pk_bf16_f32 v26, v26, v27
	v_cvt_pk_bf16_f32 v27, v34, v35
	v_pk_mul_f32 v[34:35], v[38:39], v[42:43]
	s_nop 0
	v_pk_fma_f32 v[22:23], v[22:23], v[28:29], v[34:35]
	v_pk_mul_f32 v[28:29], v[40:41], v[44:45]
	v_cvt_pk_bf16_f32 v22, v22, v23
	v_pk_fma_f32 v[24:25], v[24:25], v[36:37], v[28:29]
	s_nop 0
	v_cvt_pk_bf16_f32 v23, v24, v25
	v_add_u32_e32 v24, v47, v71
	ds_write_b64 v24, v[26:27]
	v_add_u32_e32 v24, v47, v100
	ds_write_b64 v24, v[22:23]
	ds_read_b128 v[22:25], v46 offset:128
	ds_read_b128 v[26:29], v46 offset:144
	v_lshlrev_b32_e32 v46, 2, v82
	v_or_b32_e32 v42, 2, v46
	s_waitcnt lgkmcnt(1)
	v_mov_b32_e32 v35, v24
	v_mov_b32_e32 v24, v23
	s_waitcnt lgkmcnt(0)
	v_mov_b32_e32 v37, v28
	v_mov_b32_e32 v28, v27
	v_mov_b32_e32 v34, v22
	v_pk_mul_f32 v[22:23], v[30:31], v[24:25]
	v_mov_b32_e32 v36, v26
	v_pk_mul_f32 v[26:27], v[32:33], v[28:29]
	v_pk_fma_f32 v[22:23], v[18:19], v[34:35], v[22:23] neg_lo:[0,0,1] neg_hi:[0,0,1]
	v_pk_fma_f32 v[26:27], v[20:21], v[36:37], v[26:27] neg_lo:[0,0,1] neg_hi:[0,0,1]
	v_cvt_pk_bf16_f32 v22, v22, v23
	v_cvt_pk_bf16_f32 v23, v26, v27
	v_pk_mul_f32 v[26:27], v[30:31], v[34:35]
	s_nop 0
	v_pk_fma_f32 v[18:19], v[18:19], v[24:25], v[26:27]
	v_pk_mul_f32 v[24:25], v[32:33], v[36:37]
	v_cvt_pk_bf16_f32 v18, v18, v19
	v_pk_fma_f32 v[20:21], v[20:21], v[28:29], v[24:25]
	v_bitop3_b32 v27, v81, v46, 4 bitop3:0x72
	v_cvt_pk_bf16_f32 v19, v20, v21
	v_add_u32_e32 v20, v47, v83
	ds_write_b64 v20, v[22:23]
	v_add_u32_e32 v20, v47, v94
	ds_write_b64 v20, v[18:19]
	v_and_b32_e32 v18, 0xfffffcf, v78
	v_mul_lo_u32 v18, v18, s10
	v_add_u32_e32 v26, 0, v18
	v_and_or_b32 v18, v46, 4, v81
	v_lshl_add_u32 v18, v18, 4, v26
	s_waitcnt lgkmcnt(0)
	s_barrier
	ds_read_b128 v[18:21], v18
	v_lshl_add_u32 v26, v27, 4, v26
	ds_read_b128 v[26:29], v26
	s_waitcnt vmcnt(3) lgkmcnt(1)
	v_mfma_f32_16x16x32_bf16 v[22:25], v[18:21], v[10:13], 0
	v_or_b32_e32 v47, 4, v81
	s_waitcnt vmcnt(1)
	v_mfma_f32_16x16x32_bf16 v[18:21], v[18:21], v[14:17], 0
	s_waitcnt lgkmcnt(0)
	v_mfma_f32_16x16x32_bf16 v[38:41], v[26:29], v[6:9], v[22:25]
	s_waitcnt vmcnt(0)
	v_mfma_f32_16x16x32_bf16 v[34:37], v[26:29], v[2:5], v[18:21]
	v_or_b32_e32 v26, 1, v46
	v_or_b32_e32 v46, 3, v46
	s_nop 1
	v_lshl_or_b32 v18, v26, 4, v80
	v_mul_lo_u32 v18, v18, s10
	v_add_u32_e32 v27, 0, v18
	v_bitop3_b32 v18, v26, v81, 5 bitop3:0x6c
	v_lshl_add_u32 v18, v18, 4, v27
	ds_read_b128 v[18:21], v18
	v_bitop3_b32 v26, v26, v47, 5 bitop3:0x6c
	v_lshl_add_u32 v26, v26, 4, v27
	ds_read_b128 v[26:29], v26
	s_waitcnt lgkmcnt(1)
	v_mfma_f32_16x16x32_bf16 v[22:25], v[18:21], v[10:13], 0
	v_mfma_f32_16x16x32_bf16 v[18:21], v[18:21], v[14:17], 0
	s_waitcnt lgkmcnt(0)
	v_mfma_f32_16x16x32_bf16 v[30:33], v[26:29], v[6:9], v[22:25]
	v_mfma_f32_16x16x32_bf16 v[26:29], v[26:29], v[2:5], v[18:21]
	s_nop 4
	v_lshl_or_b32 v18, v42, 4, v80
	v_mul_lo_u32 v18, v18, s10
	v_add_u32_e32 v43, 0, v18
	v_bitop3_b32 v18, v42, v81, 6 bitop3:0x6c
	v_lshl_add_u32 v18, v18, 4, v43
	ds_read_b128 v[18:21], v18
	v_bitop3_b32 v42, v42, v47, 6 bitop3:0x6c
	v_lshl_add_u32 v42, v42, 4, v43
	ds_read_b128 v[42:45], v42
	s_waitcnt lgkmcnt(1)
	v_mfma_f32_16x16x32_bf16 v[22:25], v[18:21], v[10:13], 0
	v_mfma_f32_16x16x32_bf16 v[18:21], v[18:21], v[14:17], 0
	s_waitcnt lgkmcnt(0)
	v_mfma_f32_16x16x32_bf16 v[22:25], v[42:45], v[6:9], v[22:25]
	v_mfma_f32_16x16x32_bf16 v[18:21], v[42:45], v[2:5], v[18:21]
	v_lshl_or_b32 v42, v46, 4, v80
	v_mul_lo_u32 v42, v42, s10
	v_add_u32_e32 v48, 0, v42
	v_bitop3_b32 v42, v46, v81, 7 bitop3:0x6c
	v_lshl_add_u32 v42, v42, 4, v48
	ds_read_b128 v[42:45], v42
	s_waitcnt lgkmcnt(0)
	v_mfma_f32_16x16x32_bf16 v[10:13], v[42:45], v[10:13], 0
	v_mfma_f32_16x16x32_bf16 v[14:17], v[42:45], v[14:17], 0
	v_bitop3_b32 v42, v46, v47, 7 bitop3:0x6c
	v_lshl_add_u32 v42, v42, 4, v48
	ds_read_b128 v[42:45], v42
	s_waitcnt lgkmcnt(0)
	v_mfma_f32_16x16x32_bf16 v[6:9], v[42:45], v[6:9], v[10:13]
	s_nop 2
	v_and_b32_e32 v13, 64, v1
	v_lshlrev_b32_e32 v10, 3, v82
	v_xor_b32_e32 v11, 16, v1
	v_add_u32_e32 v13, 64, v13
	v_add3_u32 v10, v10, s1, v79
	v_cmp_lt_i32_e32 vcc, v11, v13
	v_or_b32_e32 v10, v10, v76
	v_mfma_f32_16x16x32_bf16 v[2:5], v[42:45], v[2:5], v[14:17]
	v_cndmask_b32_e32 v11, v1, v11, vcc
	s_lshl_b32 s1, s7, 2
	v_bfe_u32 v12, v78, 4, 1
	v_lshlrev_b32_e32 v14, 2, v11
	v_pk_mul_f32 v[16:17], v[38:39], s[88:89] op_sel_hi:[1,0]
	v_pk_mul_f32 v[38:39], v[40:41], s[88:89] op_sel_hi:[1,0]
	v_ashrrev_i32_e32 v11, 31, v10
	v_cvt_pk_bf16_f32 v16, v16, v17
	v_cvt_pk_bf16_f32 v17, v38, v39
	v_lshlrev_b64 v[38:39], 11, v[10:11]
	s_add_u32 s22, s24, s1
	v_lshl_add_u64 v[38:39], s[84:85], 0, v[38:39]
	s_mov_b32 s1, s69
	v_lshl_add_u64 v[38:39], v[38:39], 0, s[0:1]
	v_lshlrev_b32_e32 v98, 3, v12
	v_lshl_add_u64 v[38:39], v[38:39], 0, v[98:99]
	s_mov_b32 s0, 0x1b00000
	v_add_co_u32_e32 v38, vcc, s0, v38
	v_and_b32_e32 v15, 0xffff0000, v16
	s_nop 0
	v_addc_co_u32_e32 v39, vcc, 0, v39, vcc
	global_store_dwordx2 v[38:39], v[16:17], off offset:1024
	v_lshlrev_b32_e32 v13, 16, v16
	v_mul_f32_e32 v15, v15, v15
	v_and_b32_e32 v16, 0xffff0000, v17
	v_fmac_f32_e32 v15, v13, v13
	v_lshlrev_b32_e32 v13, 16, v17
	v_mul_f32_e32 v16, v16, v16
	v_fmac_f32_e32 v16, v13, v13
	v_add_f32_e32 v13, v15, v16
	v_mov_b32_e32 v15, v13
	s_nop 1
	v_permlane16_swap_b32_e32 v13, v15
	v_cmp_eq_u32_e64 s[38:39], 0, v12
	s_addc_u32 s23, s25, 0
	s_and_saveexec_b64 s[0:1], s[38:39]
	s_cbranch_execz .LBB0_805
	v_lshlrev_b64 v[16:17], 7, v[10:11]
	s_waitcnt lgkmcnt(0)
	v_add_f32_e32 v13, v13, v15
	v_lshl_add_u64 v[16:17], s[22:23], 0, v[16:17]
	global_store_dword v[16:17], v13, off
